# stat-exchange protocol ops (store, atomic, polls, partner loads) flat -> global
# speedup vs baseline: 1.0029x; 1.0029x over previous
;     __device__ __forceinline__ void fused(f32x4 (&acc)[2][2][4][2], const Unit& u, int wr, int wc, int fr, int fq, LAS unsigned char* lds, int tid) const {
;     ...
;         asm volatile("s_waitcnt lgkmcnt(0)" ::: "memory"); __builtin_amdgcn_s_barrier(); asm volatile("" ::: "memory");
;         if (tid < 256) { const float t_ = (P[tid * 4 + 0] + P[tid * 4 + 1]) + (P[tid * 4 + 2] + P[tid * 4 + 3]);
;             __hip_atomic_store(xbuf + ((size_t)u.pm * BM + tid) * 4 + u.pn, t_, __ATOMIC_RELAXED, __HIP_MEMORY_SCOPE_AGENT); }
;         asm volatile("s_waitcnt vmcnt(0)" ::: "memory"); __builtin_amdgcn_s_barrier(); asm volatile("" ::: "memory");
;         if (tid == 0) { __hip_atomic_fetch_add(cnt + u.pm, 1u, __ATOMIC_RELAXED, __HIP_MEMORY_SCOPE_AGENT);
.LBB0_495:
	s_or_b64 exec, exec, s[4:5]
	s_waitcnt lgkmcnt(0)
	s_barrier
	s_movk_i32 s4, 0x100
	v_cmp_gt_i32_e32 vcc, s4, v128
	s_and_saveexec_b64 s[4:5], vcc
	s_cbranch_execz .LBB0_497
	v_add_u32_e32 v0, 0, v178
	s_waitcnt lgkmcnt(0)
	ds_read_b128 v[0:3], v0
	s_lshl_b64 s[14:15], s[22:23], 12
	s_add_u32 s14, s38, s14
	s_addc_u32 s15, s39, s15
	s_ashr_i32 s25, s24, 31
	s_waitcnt lgkmcnt(0)
	v_mov_b32_e32 v4, v1
	v_mov_b32_e32 v5, v2
	v_mov_b32_e32 v1, v3
	v_pk_add_f32 v[0:1], v[4:5], v[0:1]
	v_lshl_add_u64 v[2:3], v[128:129], 4, s[14:15]
	v_pk_add_f32 v[0:1], v[0:1], v[0:1] op_sel:[0,1] op_sel_hi:[1,0]
	v_lshl_add_u64 v[2:3], s[24:25], 2, v[2:3]
	global_store_dword v[2:3], v0, off sc1
.LBB0_497:
	s_or_b64 exec, exec, s[4:5]
	s_waitcnt vmcnt(0)
	s_barrier
	v_cmp_eq_u32_e64 s[4:5], 0, v128
	s_and_saveexec_b64 s[24:25], s[4:5]
	s_cbranch_execz .LBB0_520
	s_lshl_b64 s[4:5], s[22:23], 2
	s_add_u32 s2, s2, s4
	s_addc_u32 s3, s3, s5
	v_mov_b32_e32 v2, 1
	s_waitcnt lgkmcnt(0)
	v_mov_b64_e32 v[0:1], s[2:3]
	global_atomic_add v[0:1], v2, off
	s_mov_b32 s9, 0x1000000
	s_mov_b64 s[2:3], 0
	s_branch .LBB0_508

;     __device__ __forceinline__ void fused(f32x4 (&acc)[2][2][4][2], const Unit& u, int wr, int wc, int fr, int fq, LAS unsigned char* lds, int tid) const {
;     ...
;         if (tid == 0) { __hip_atomic_fetch_add(cnt + u.pm, 1u, __ATOMIC_RELAXED, __HIP_MEMORY_SCOPE_AGENT);
;             unsigned sp = 0; while (__hip_atomic_load(cnt + u.pm, __ATOMIC_RELAXED, __HIP_MEMORY_SCOPE_AGENT) < 4u) { __builtin_amdgcn_s_sleep(1); if (++sp > (1u << 24)) break; }
;             __builtin_amdgcn_fence(__ATOMIC_ACQUIRE, "agent"); asm volatile("s_waitcnt vmcnt(0)" ::: "memory"); }
.LBB0_508:
	global_load_dword v2, v[0:1], off sc1
	s_or_b64 s[40:41], s[40:41], exec
	s_waitcnt vmcnt(0) lgkmcnt(0)
	v_cmp_gt_u32_e64 s[4:5], 4, v2
	s_and_saveexec_b64 s[42:43], s[4:5]
	s_cbranch_execz .LBB0_507
	s_cmp_lg_u32 s9, 0
	s_sleep 1
	s_cbranch_scc0 .LBB0_518
	global_load_dword v2, v[0:1], off sc1
	s_mov_b64 s[46:47], -1
	s_waitcnt vmcnt(0) lgkmcnt(0)
	v_cmp_gt_u32_e64 s[4:5], 4, v2
	s_and_saveexec_b64 s[44:45], s[4:5]
	s_cbranch_execz .LBB0_505
	s_sleep 1
	global_load_dword v2, v[0:1], off sc1
	s_mov_b64 s[48:49], -1
	s_waitcnt vmcnt(0) lgkmcnt(0)
	v_cmp_gt_u32_e64 s[4:5], 4, v2
	s_and_saveexec_b64 s[46:47], s[4:5]
	s_cbranch_execz .LBB0_504
	s_sleep 1
	global_load_dword v2, v[0:1], off sc1
	s_mov_b64 s[50:51], -1
	s_waitcnt vmcnt(0) lgkmcnt(0)
	v_cmp_gt_u32_e64 s[4:5], 4, v2
	s_and_saveexec_b64 s[48:49], s[4:5]
	s_cbranch_execz .LBB0_503
	s_sleep 1
	global_load_dword v2, v[0:1], off sc1
	s_mov_b64 s[52:53], -1
	s_waitcnt vmcnt(0) lgkmcnt(0)
	v_cmp_gt_u32_e64 s[4:5], 4, v2
	s_and_saveexec_b64 s[50:51], s[4:5]
	s_cbranch_execz .LBB0_502
	s_sleep 1
	global_load_dword v2, v[0:1], off sc1
	s_mov_b64 s[54:55], -1
	s_waitcnt vmcnt(0) lgkmcnt(0)
	v_cmp_gt_u32_e64 s[4:5], 4, v2
	s_and_saveexec_b64 s[52:53], s[4:5]
	s_cbranch_execz .LBB0_501
	s_sleep 1
	global_load_dword v2, v[0:1], off sc1
	s_mov_b64 s[56:57], -1
	s_waitcnt vmcnt(0) lgkmcnt(0)
	v_cmp_gt_u32_e64 s[4:5], 4, v2
	s_and_saveexec_b64 s[54:55], s[4:5]
	s_cbranch_execz .LBB0_500
	s_sleep 1
	global_load_dword v2, v[0:1], off sc1
	s_waitcnt vmcnt(0) lgkmcnt(0)
	v_cmp_gt_u32_e64 s[4:5], 4, v2
	s_and_saveexec_b64 s[58:59], s[4:5]
	s_cbranch_execz .LBB0_499
	s_add_i32 s9, s9, -8
	s_xor_b64 s[56:57], exec, -1
	s_sleep 1
	s_branch .LBB0_499

;     __device__ __forceinline__ void fused(f32x4 (&acc)[2][2][4][2], const Unit& u, int wr, int wc, int fr, int fq, LAS unsigned char* lds, int tid) const {
;     ...
;         if (tid < 256) { const float* sl = xbuf + ((size_t)u.pm * BM + tid) * 4; float t_ = 0.f;
; #pragma unroll
;             for (int k = 0; k < 4; ++k) t_ += __hip_atomic_load(sl + k, __ATOMIC_RELAXED, __HIP_MEMORY_SCOPE_AGENT);
;             S[tid] = 1.0f / sqrtf(t_ * (1.0f / DM) + RMS_EPS); }
.LBB0_520:
	s_or_b64 exec, exec, s[24:25]
	s_barrier
	s_lshl_b64 s[2:3], s[22:23], 18
	s_and_saveexec_b64 s[24:25], vcc
	s_cbranch_execz .LBB0_522
	s_lshl_b64 s[4:5], s[22:23], 12
	s_add_u32 s4, s38, s4
	s_addc_u32 s5, s39, s5
	s_waitcnt lgkmcnt(0)
	v_lshl_add_u64 v[0:1], v[128:129], 4, s[4:5]
	global_load_dword v2, v[0:1], off sc1
	global_load_dword v3, v[0:1], off offset:4 sc1
	global_load_dword v4, v[0:1], off offset:8 sc1
	s_nop 0
	global_load_dword v0, v[0:1], off offset:12 sc1
	v_mov_b32_e32 v1, 0x358637bd
	s_mov_b32 s4, 0xf800000
	s_waitcnt vmcnt(0) lgkmcnt(0)
	v_add_f32_e32 v2, 0, v2
	v_add_f32_e32 v2, v2, v3
	v_add_f32_e32 v2, v2, v4
	v_add_f32_e32 v0, v2, v0
	v_fmac_f32_e32 v1, 0x3a800000, v0
	v_mul_f32_e32 v0, 0x4f800000, v1
	v_cmp_gt_f32_e32 vcc, s4, v1
	v_mov_b32_e32 v2, 0x260
	s_nop 0
	v_cndmask_b32_e32 v0, v1, v0, vcc
	v_sqrt_f32_e32 v1, v0
	s_nop 0
	v_add_u32_e32 v3, -1, v1
	v_add_u32_e32 v4, 1, v1
	v_fma_f32 v5, -v3, v1, v0
	v_fma_f32 v6, -v4, v1, v0
	v_cmp_ge_f32_e64 s[4:5], 0, v5
	s_nop 1
	v_cndmask_b32_e64 v1, v1, v3, s[4:5]
	v_cmp_lt_f32_e64 s[4:5], 0, v6
	s_nop 1
	v_cndmask_b32_e64 v1, v1, v4, s[4:5]
	v_mul_f32_e32 v3, 0x37800000, v1
	v_cndmask_b32_e32 v1, v1, v3, vcc
	v_cmp_class_f32_e32 vcc, v0, v2
	s_nop 1
	v_cndmask_b32_e32 v0, v1, v0, vcc
	v_div_scale_f32 v1, s[4:5], v0, v0, 1.0
	v_rcp_f32_e32 v2, v1
	v_div_scale_f32 v3, vcc, 1.0, v0, 1.0
	v_fma_f32 v4, -v1, v2, 1.0
	v_fmac_f32_e32 v2, v4, v2
	v_mul_f32_e32 v4, v3, v2
	v_fma_f32 v5, -v1, v4, v3
	v_fmac_f32_e32 v4, v5, v2
	v_fma_f32 v1, -v1, v4, v3
	v_div_fmas_f32 v1, v1, v2, v4
	v_div_fixup_f32 v0, v1, v0, 1.0
	v_lshl_add_u32 v1, v128, 2, 0
	ds_write_b32 v1, v0 offset:4096

;     __device__ __forceinline__ void fused(f32x4 (&acc)[2][2][4][2], const Unit& u, int wr, int wc, int fr, int fq, LAS unsigned char* lds, int tid) const {
;     ...
;         if (tid < 256) { const float t_ = (P[tid * 4 + 0] + P[tid * 4 + 1]) + (P[tid * 4 + 2] + P[tid * 4 + 3]);
;             __hip_atomic_store(xbuf + ((size_t)u.pm * BM + tid) * 4 + u.pn, t_, __ATOMIC_RELAXED, __HIP_MEMORY_SCOPE_AGENT); }
;         asm volatile("s_waitcnt vmcnt(0)" ::: "memory"); __builtin_amdgcn_s_barrier(); asm volatile("" ::: "memory");
;         if (tid == 0) { __hip_atomic_fetch_add(cnt + u.pm, 1u, __ATOMIC_RELAXED, __HIP_MEMORY_SCOPE_AGENT);
;             unsigned sp = 0; while (__hip_atomic_load(cnt + u.pm, __ATOMIC_RELAXED, __HIP_MEMORY_SCOPE_AGENT) < 4u) { __builtin_amdgcn_s_sleep(1); if (++sp > (1u << 24)) break; }
.LBB0_1124:
	s_or_b64 exec, exec, s[2:3]
	s_waitcnt lgkmcnt(0)
	s_barrier
	s_movk_i32 s1, 0x100
	v_cmp_gt_i32_e32 vcc, s1, v144
	s_and_saveexec_b64 s[2:3], vcc
	s_cbranch_execz .LBB0_1126
	v_add_u32_e32 v0, 0, v190
	s_waitcnt lgkmcnt(0)
	ds_read_b128 v[0:3], v0
	s_lshl_b64 s[14:15], s[6:7], 12
	s_add_u32 s14, s28, s14
	s_addc_u32 s15, s29, s15
	s_ashr_i32 s1, s0, 31
	s_waitcnt lgkmcnt(0)
	v_mov_b32_e32 v4, v1
	v_mov_b32_e32 v5, v2
	v_mov_b32_e32 v1, v3
	v_pk_add_f32 v[0:1], v[4:5], v[0:1]
	v_lshl_add_u64 v[2:3], v[144:145], 4, s[14:15]
	v_pk_add_f32 v[0:1], v[0:1], v[0:1] op_sel:[0,1] op_sel_hi:[1,0]
	v_lshl_add_u64 v[2:3], s[0:1], 2, v[2:3]
	global_store_dword v[2:3], v0, off sc1
.LBB0_1126:
	s_or_b64 exec, exec, s[2:3]
	s_waitcnt vmcnt(0)
	s_barrier
	v_cmp_eq_u32_e64 s[0:1], 0, v144
	s_and_saveexec_b64 s[2:3], s[0:1]
	s_cbranch_execz .LBB0_1149
	s_lshl_b64 s[0:1], s[6:7], 2
	s_add_u32 s0, s30, s0
	s_addc_u32 s1, s31, s1
	v_mov_b32_e32 v2, 1
	s_waitcnt lgkmcnt(0)
	v_mov_b64_e32 v[0:1], s[0:1]
	global_atomic_add v[0:1], v2, off
	s_mov_b32 s14, 0x1000000
	s_mov_b64 s[30:31], 0
	s_branch .LBB0_1137

;     __device__ __forceinline__ void fused(f32x4 (&acc)[2][2][4][2], const Unit& u, int wr, int wc, int fr, int fq, LAS unsigned char* lds, int tid) const {
;     ...
;         if (tid == 0) { __hip_atomic_fetch_add(cnt + u.pm, 1u, __ATOMIC_RELAXED, __HIP_MEMORY_SCOPE_AGENT);
;             unsigned sp = 0; while (__hip_atomic_load(cnt + u.pm, __ATOMIC_RELAXED, __HIP_MEMORY_SCOPE_AGENT) < 4u) { __builtin_amdgcn_s_sleep(1); if (++sp > (1u << 24)) break; }
;             __builtin_amdgcn_fence(__ATOMIC_ACQUIRE, "agent"); asm volatile("s_waitcnt vmcnt(0)" ::: "memory"); }
.LBB0_1137:
	global_load_dword v2, v[0:1], off sc1
	s_or_b64 s[34:35], s[34:35], exec
	s_waitcnt vmcnt(0) lgkmcnt(0)
	v_cmp_gt_u32_e64 s[0:1], 4, v2
	s_and_saveexec_b64 s[36:37], s[0:1]
	s_cbranch_execz .LBB0_1136
	s_cmp_lg_u32 s14, 0
	s_sleep 1
	s_cbranch_scc0 .LBB0_1147
	global_load_dword v2, v[0:1], off sc1
	s_mov_b64 s[40:41], -1
	s_waitcnt vmcnt(0) lgkmcnt(0)
	v_cmp_gt_u32_e64 s[0:1], 4, v2
	s_and_saveexec_b64 s[38:39], s[0:1]
	s_cbranch_execz .LBB0_1134
	s_sleep 1
	global_load_dword v2, v[0:1], off sc1
	s_mov_b64 s[42:43], -1
	s_waitcnt vmcnt(0) lgkmcnt(0)
	v_cmp_gt_u32_e64 s[0:1], 4, v2
	s_and_saveexec_b64 s[40:41], s[0:1]
	s_cbranch_execz .LBB0_1133
	s_sleep 1
	global_load_dword v2, v[0:1], off sc1
	s_mov_b64 s[44:45], -1
	s_waitcnt vmcnt(0) lgkmcnt(0)
	v_cmp_gt_u32_e64 s[0:1], 4, v2
	s_and_saveexec_b64 s[42:43], s[0:1]
	s_cbranch_execz .LBB0_1132
	s_sleep 1
	global_load_dword v2, v[0:1], off sc1
	s_mov_b64 s[46:47], -1
	s_waitcnt vmcnt(0) lgkmcnt(0)
	v_cmp_gt_u32_e64 s[0:1], 4, v2
	s_and_saveexec_b64 s[44:45], s[0:1]
	s_cbranch_execz .LBB0_1131
	s_sleep 1
	global_load_dword v2, v[0:1], off sc1
	s_mov_b64 s[48:49], -1
	s_waitcnt vmcnt(0) lgkmcnt(0)
	v_cmp_gt_u32_e64 s[0:1], 4, v2
	s_and_saveexec_b64 s[46:47], s[0:1]
	s_cbranch_execz .LBB0_1130
	s_sleep 1
	global_load_dword v2, v[0:1], off sc1
	s_mov_b64 s[50:51], -1
	s_waitcnt vmcnt(0) lgkmcnt(0)
	v_cmp_gt_u32_e64 s[0:1], 4, v2
	s_and_saveexec_b64 s[48:49], s[0:1]
	s_cbranch_execz .LBB0_1129
	s_sleep 1
	global_load_dword v2, v[0:1], off sc1
	s_waitcnt vmcnt(0) lgkmcnt(0)
	v_cmp_gt_u32_e64 s[0:1], 4, v2
	s_and_saveexec_b64 s[52:53], s[0:1]
	s_cbranch_execz .LBB0_1128
	s_add_i32 s14, s14, -8
	s_xor_b64 s[50:51], exec, -1
	s_sleep 1
	s_branch .LBB0_1128

;     __device__ __forceinline__ void fused(f32x4 (&acc)[2][2][4][2], const Unit& u, int wr, int wc, int fr, int fq, LAS unsigned char* lds, int tid) const {
;     ...
;         if (tid < 256) { const float* sl = xbuf + ((size_t)u.pm * BM + tid) * 4; float t_ = 0.f;
; #pragma unroll
;             for (int k = 0; k < 4; ++k) t_ += __hip_atomic_load(sl + k, __ATOMIC_RELAXED, __HIP_MEMORY_SCOPE_AGENT);
;             S[tid] = 1.0f / sqrtf(t_ * (1.0f / DM) + RMS_EPS); }
.LBB0_1149:
	s_or_b64 exec, exec, s[2:3]
	s_barrier
	s_and_saveexec_b64 s[2:3], vcc
	s_cbranch_execz .LBB0_1151
	s_lshl_b64 s[0:1], s[6:7], 12
	s_add_u32 s0, s28, s0
	s_addc_u32 s1, s29, s1
	s_waitcnt lgkmcnt(0)
	v_lshl_add_u64 v[0:1], v[144:145], 4, s[0:1]
	global_load_dword v2, v[0:1], off sc1
	global_load_dword v3, v[0:1], off offset:4 sc1
	global_load_dword v4, v[0:1], off offset:8 sc1
	s_nop 0
	global_load_dword v0, v[0:1], off offset:12 sc1
	v_mov_b32_e32 v1, 0x358637bd
	s_mov_b32 s0, 0xf800000
	s_waitcnt vmcnt(0) lgkmcnt(0)
	v_add_f32_e32 v2, 0, v2
	v_add_f32_e32 v2, v2, v3
	v_add_f32_e32 v2, v2, v4
	v_add_f32_e32 v0, v2, v0
	v_fmac_f32_e32 v1, 0x3a800000, v0
	v_mul_f32_e32 v0, 0x4f800000, v1
	v_cmp_gt_f32_e32 vcc, s0, v1
	v_mov_b32_e32 v2, 0x260
	s_nop 0
	v_cndmask_b32_e32 v0, v1, v0, vcc
	v_sqrt_f32_e32 v1, v0
	s_nop 0
	v_add_u32_e32 v3, -1, v1
	v_add_u32_e32 v4, 1, v1
	v_fma_f32 v5, -v3, v1, v0
	v_fma_f32 v6, -v4, v1, v0
	v_cmp_ge_f32_e64 s[0:1], 0, v5
	s_nop 1
	v_cndmask_b32_e64 v1, v1, v3, s[0:1]
	v_cmp_lt_f32_e64 s[0:1], 0, v6
	s_nop 1
	v_cndmask_b32_e64 v1, v1, v4, s[0:1]
	v_mul_f32_e32 v3, 0x37800000, v1
	v_cndmask_b32_e32 v1, v1, v3, vcc
	v_cmp_class_f32_e32 vcc, v0, v2
	s_nop 1
	v_cndmask_b32_e32 v0, v1, v0, vcc
	v_div_scale_f32 v1, s[0:1], v0, v0, 1.0
	v_rcp_f32_e32 v2, v1
	v_div_scale_f32 v3, vcc, 1.0, v0, 1.0
	v_fma_f32 v4, -v1, v2, 1.0
	v_fmac_f32_e32 v2, v4, v2
	v_mul_f32_e32 v4, v3, v2
	v_fma_f32 v5, -v1, v4, v3
	v_fmac_f32_e32 v4, v5, v2
	v_fma_f32 v1, -v1, v4, v3
	v_div_fmas_f32 v1, v1, v2, v4
	v_div_fixup_f32 v0, v1, v0, 1.0
	v_lshl_add_u32 v1, v144, 2, 0
	ds_write_b32 v1, v0 offset:4096

;     __device__ __forceinline__ void fused(f32x4 (&acc)[2][2][4][2], const Unit& u, int wr, int wc, int fr, int fq, LAS unsigned char* lds, int tid) const {
;     ...
;         if (tid < 256) { const float t_ = (P[tid * 4 + 0] + P[tid * 4 + 1]) + (P[tid * 4 + 2] + P[tid * 4 + 3]);
;             __hip_atomic_store(xbuf + ((size_t)u.pm * BM + tid) * 4 + u.pn, t_, __ATOMIC_RELAXED, __HIP_MEMORY_SCOPE_AGENT); }
;         asm volatile("s_waitcnt vmcnt(0)" ::: "memory"); __builtin_amdgcn_s_barrier(); asm volatile("" ::: "memory");
;         if (tid == 0) { __hip_atomic_fetch_add(cnt + u.pm, 1u, __ATOMIC_RELAXED, __HIP_MEMORY_SCOPE_AGENT);
;             unsigned sp = 0; while (__hip_atomic_load(cnt + u.pm, __ATOMIC_RELAXED, __HIP_MEMORY_SCOPE_AGENT) < 4u) { __builtin_amdgcn_s_sleep(1); if (++sp > (1u << 24)) break; }
.LBB0_1416:
	s_or_b64 exec, exec, s[18:19]
	s_waitcnt lgkmcnt(0)
	s_barrier
	s_movk_i32 s1, 0x100
	v_cmp_gt_i32_e32 vcc, s1, v128
	s_and_saveexec_b64 s[18:19], vcc
	s_cbranch_execz .LBB0_1418
	v_add_u32_e32 v0, 0, v166
	s_waitcnt lgkmcnt(0)
	ds_read_b128 v[0:3], v0
	s_lshl_b64 s[12:13], s[6:7], 12
	s_add_u32 s12, s10, s12
	s_addc_u32 s13, s11, s13
	s_ashr_i32 s1, s0, 31
	s_waitcnt lgkmcnt(0)
	v_mov_b32_e32 v4, v1
	v_mov_b32_e32 v5, v2
	v_mov_b32_e32 v1, v3
	v_pk_add_f32 v[0:1], v[4:5], v[0:1]
	v_lshl_add_u64 v[2:3], v[128:129], 4, s[12:13]
	v_pk_add_f32 v[0:1], v[0:1], v[0:1] op_sel:[0,1] op_sel_hi:[1,0]
	v_lshl_add_u64 v[2:3], s[0:1], 2, v[2:3]
	global_store_dword v[2:3], v0, off sc1
.LBB0_1418:
	s_or_b64 exec, exec, s[18:19]
	s_waitcnt vmcnt(0)
	s_barrier
	v_cmp_eq_u32_e64 s[0:1], 0, v128
	s_and_saveexec_b64 s[18:19], s[0:1]
	s_cbranch_execz .LBB0_1441
	s_lshl_b64 s[0:1], s[6:7], 2
	s_add_u32 s0, s16, s0
	s_addc_u32 s1, s17, s1
	v_mov_b32_e32 v2, 1
	s_waitcnt lgkmcnt(0)
	v_mov_b64_e32 v[0:1], s[0:1]
	global_atomic_add v[0:1], v2, off
	s_mov_b32 s12, 0x1000000
	s_mov_b64 s[16:17], 0
	s_branch .LBB0_1429

;     __device__ __forceinline__ void fused(f32x4 (&acc)[2][2][4][2], const Unit& u, int wr, int wc, int fr, int fq, LAS unsigned char* lds, int tid) const {
;     ...
;         if (tid == 0) { __hip_atomic_fetch_add(cnt + u.pm, 1u, __ATOMIC_RELAXED, __HIP_MEMORY_SCOPE_AGENT);
;             unsigned sp = 0; while (__hip_atomic_load(cnt + u.pm, __ATOMIC_RELAXED, __HIP_MEMORY_SCOPE_AGENT) < 4u) { __builtin_amdgcn_s_sleep(1); if (++sp > (1u << 24)) break; }
;             __builtin_amdgcn_fence(__ATOMIC_ACQUIRE, "agent"); asm volatile("s_waitcnt vmcnt(0)" ::: "memory"); }
.LBB0_1429:
	global_load_dword v2, v[0:1], off sc1
	s_or_b64 s[20:21], s[20:21], exec
	s_waitcnt vmcnt(0) lgkmcnt(0)
	v_cmp_gt_u32_e64 s[0:1], 4, v2
	s_and_saveexec_b64 s[22:23], s[0:1]
	s_cbranch_execz .LBB0_1428
	s_cmp_lg_u32 s12, 0
	s_sleep 1
	s_cbranch_scc0 .LBB0_1439
	global_load_dword v2, v[0:1], off sc1
	s_mov_b64 s[26:27], -1
	s_waitcnt vmcnt(0) lgkmcnt(0)
	v_cmp_gt_u32_e64 s[0:1], 4, v2
	s_and_saveexec_b64 s[24:25], s[0:1]
	s_cbranch_execz .LBB0_1426
	s_sleep 1
	global_load_dword v2, v[0:1], off sc1
	s_mov_b64 s[28:29], -1
	s_waitcnt vmcnt(0) lgkmcnt(0)
	v_cmp_gt_u32_e64 s[0:1], 4, v2
	s_and_saveexec_b64 s[26:27], s[0:1]
	s_cbranch_execz .LBB0_1425
	s_sleep 1
	global_load_dword v2, v[0:1], off sc1
	s_mov_b64 s[30:31], -1
	s_waitcnt vmcnt(0) lgkmcnt(0)
	v_cmp_gt_u32_e64 s[0:1], 4, v2
	s_and_saveexec_b64 s[28:29], s[0:1]
	s_cbranch_execz .LBB0_1424
	s_sleep 1
	global_load_dword v2, v[0:1], off sc1
	s_mov_b64 s[34:35], -1
	s_waitcnt vmcnt(0) lgkmcnt(0)
	v_cmp_gt_u32_e64 s[0:1], 4, v2
	s_and_saveexec_b64 s[30:31], s[0:1]
	s_cbranch_execz .LBB0_1423
	s_sleep 1
	global_load_dword v2, v[0:1], off sc1
	s_mov_b64 s[36:37], -1
	s_waitcnt vmcnt(0) lgkmcnt(0)
	v_cmp_gt_u32_e64 s[0:1], 4, v2
	s_and_saveexec_b64 s[34:35], s[0:1]
	s_cbranch_execz .LBB0_1422
	s_sleep 1
	global_load_dword v2, v[0:1], off sc1
	s_mov_b64 s[38:39], -1
	s_waitcnt vmcnt(0) lgkmcnt(0)
	v_cmp_gt_u32_e64 s[0:1], 4, v2
	s_and_saveexec_b64 s[36:37], s[0:1]
	s_cbranch_execz .LBB0_1421
	s_sleep 1
	global_load_dword v2, v[0:1], off sc1
	s_waitcnt vmcnt(0) lgkmcnt(0)
	v_cmp_gt_u32_e64 s[0:1], 4, v2
	s_and_saveexec_b64 s[40:41], s[0:1]
	s_cbranch_execz .LBB0_1420
	s_add_i32 s12, s12, -8
	s_xor_b64 s[38:39], exec, -1
	s_sleep 1
	s_branch .LBB0_1420

;     __device__ __forceinline__ void fused(f32x4 (&acc)[2][2][4][2], const Unit& u, int wr, int wc, int fr, int fq, LAS unsigned char* lds, int tid) const {
;     ...
;         if (tid < 256) { const float* sl = xbuf + ((size_t)u.pm * BM + tid) * 4; float t_ = 0.f;
; #pragma unroll
;             for (int k = 0; k < 4; ++k) t_ += __hip_atomic_load(sl + k, __ATOMIC_RELAXED, __HIP_MEMORY_SCOPE_AGENT);
;             S[tid] = 1.0f / sqrtf(t_ * (1.0f / DM) + RMS_EPS); }
.LBB0_1441:
	s_or_b64 exec, exec, s[18:19]
	s_barrier
	s_lshl_b64 s[16:17], s[6:7], 18
	s_and_saveexec_b64 s[18:19], vcc
	s_cbranch_execz .LBB0_1443
	s_lshl_b64 s[0:1], s[6:7], 12
	s_add_u32 s0, s10, s0
	s_addc_u32 s1, s11, s1
	s_waitcnt lgkmcnt(0)
	v_lshl_add_u64 v[0:1], v[128:129], 4, s[0:1]
	global_load_dword v2, v[0:1], off sc1
	global_load_dword v3, v[0:1], off offset:4 sc1
	global_load_dword v4, v[0:1], off offset:8 sc1
	s_nop 0
	global_load_dword v0, v[0:1], off offset:12 sc1
	v_mov_b32_e32 v1, 0x358637bd
	s_mov_b32 s0, 0xf800000
	s_waitcnt vmcnt(0) lgkmcnt(0)
	v_add_f32_e32 v2, 0, v2
	v_add_f32_e32 v2, v2, v3
	v_add_f32_e32 v2, v2, v4
	v_add_f32_e32 v0, v2, v0
	v_fmac_f32_e32 v1, 0x3a800000, v0
	v_mul_f32_e32 v0, 0x4f800000, v1
	v_cmp_gt_f32_e32 vcc, s0, v1
	v_mov_b32_e32 v2, 0x260
	s_nop 0
	v_cndmask_b32_e32 v0, v1, v0, vcc
	v_sqrt_f32_e32 v1, v0
	s_nop 0
	v_add_u32_e32 v3, -1, v1
	v_add_u32_e32 v4, 1, v1
	v_fma_f32 v5, -v3, v1, v0
	v_fma_f32 v6, -v4, v1, v0
	v_cmp_ge_f32_e64 s[0:1], 0, v5
	s_nop 1
	v_cndmask_b32_e64 v1, v1, v3, s[0:1]
	v_cmp_lt_f32_e64 s[0:1], 0, v6
	s_nop 1
	v_cndmask_b32_e64 v1, v1, v4, s[0:1]
	v_mul_f32_e32 v3, 0x37800000, v1
	v_cndmask_b32_e32 v1, v1, v3, vcc
	v_cmp_class_f32_e32 vcc, v0, v2
	s_nop 1
	v_cndmask_b32_e32 v0, v1, v0, vcc
	v_div_scale_f32 v1, s[0:1], v0, v0, 1.0
	v_rcp_f32_e32 v2, v1
	v_div_scale_f32 v3, vcc, 1.0, v0, 1.0
	v_fma_f32 v4, -v1, v2, 1.0
	v_fmac_f32_e32 v2, v4, v2
	v_mul_f32_e32 v4, v3, v2
	v_fma_f32 v5, -v1, v4, v3
	v_fmac_f32_e32 v4, v5, v2
	v_fma_f32 v1, -v1, v4, v3
	v_div_fmas_f32 v1, v1, v2, v4
	v_div_fixup_f32 v0, v1, v0, 1.0
	v_lshl_add_u32 v1, v128, 2, 0
	ds_write_b32 v1, v0 offset:4096
